# PH5: first queue round dealt statically (attention half-units XCD-local by K/V head), later items from the queue
# speedup vs baseline: 1.0098x; 1.0015x over previous
.LBB0_1834:
	s_cmp_lt_i32 s24, 6
	s_cselect_b64 s[0:1], -1, 0
	s_and_b64 s[46:47], s[0:1], s[2:3]
	s_andn2_b64 vcc, exec, s[46:47]
	s_cbranch_vccnz .LBB0_2236
	s_mov_b64 s[4:5], s[24:25]
	s_mov_b64 s[6:7], s[26:27]
	s_lshl_b32 s0, s6, 6
	s_ashr_i32 s1, s0, 31
	s_and_b32 s38, s33, 0xffffffc0
	s_lshl_b64 s[0:1], s[0:1], 2
	s_add_u32 s36, s50, s0
	s_addc_u32 s37, s51, s1
	s_add_u32 s52, s50, 0x4000000
	s_addc_u32 s53, s51, 0
	s_add_u32 s0, s50, 0x4900000
	v_writelane_b32 v254, s0, 29
	s_addc_u32 s0, s51, 0
	v_writelane_b32 v254, s0, 31
	s_add_u32 s0, s50, 0x340000
	v_writelane_b32 v254, s0, 33
	s_addc_u32 s0, s51, 0
	v_writelane_b32 v254, s0, 34
	s_add_u32 s54, s50, 0xf300000
	v_readlane_b32 s1, v254, 21
	s_mul_i32 s0, s1, 0x2800
	s_addc_u32 s55, s51, 0
	s_add_i32 s92, s0, 0
	s_mul_i32 s0, s1, 0x1800
	s_add_i32 s69, s92, s0
	s_add_i32 s0, s1, 0x8a0
	s_add_u32 s90, s50, 0x4100000
	s_addc_u32 s91, s51, 0
	s_add_u32 s48, s50, 0x300000
	v_writelane_b32 v254, s0, 35
	s_addc_u32 s49, s51, 0
	s_bfe_u32 s0, s33, 0x20006
	s_mov_b32 s45, s0
	s_mul_i32 s0, s0, 0x8080
	s_lshr_b32 s35, s33, 8
	s_add_i32 s39, s0, 0
	s_cmpk_lt_u32 s33, 0x100
	s_cselect_b64 s[70:71], -1, 0
	s_cmpk_gt_u32 s33, 0xff
	s_cselect_b64 s[0:1], -1, 0
	v_writelane_b32 v254, s0, 25
	v_mbcnt_lo_u32_b32 v0, -1, 0
	v_mbcnt_hi_u32_b32 v0, -1, v0
	s_mulk_i32 s35, 0x1020
	v_sub_u32_e32 v0, 0, v0
	v_writelane_b32 v254, s1, 26
	s_add_u32 s0, s50, 0x9800000
	v_writelane_b32 v254, s0, 27
	s_addc_u32 s0, s51, 0
	v_writelane_b32 v255, s0, 63
	s_lshl_b32 s0, s6, 13
	s_ashr_i32 s1, s0, 31
	s_lshl_b64 s[0:1], s[0:1], 2
	s_add_u32 s0, s50, s0
	s_addc_u32 s1, s51, s1
	s_add_u32 s0, s0, 0x10000
	v_writelane_b32 v254, s0, 23
	s_addc_u32 s0, s1, 0
	s_add_u32 s66, s50, 0xe100000
	v_writelane_b32 v254, s0, 37
	s_addc_u32 s67, s51, 0
	s_add_i32 s0, s92, 0x400
	v_cmp_eq_u32_e64 s[2:3], s38, v0
	v_writelane_b32 v254, s0, 38
	s_add_i32 s0, s92, 0x1e0
	v_mov_b32_e32 v161, 0
	s_add_i32 s94, 0, 0x27f40
	v_mbcnt_lo_u32_b32 v0, -1, 0
	s_mov_b32 s9, 0
	s_mov_b32 s97, 0x8080
	s_movk_i32 s44, 0x100
	v_writelane_b32 v254, s0, 39
	s_add_i32 s88, s39, s35
	s_movk_i32 s93, 0x7fff
	s_movk_i32 s68, 0xc0
	s_movk_i32 s33, 0x240
	v_mov_b32_e32 v194, 0x1000
	s_mov_b32 s95, 0xffff0000
	s_add_i32 s56, 0, 0x11c00
	s_add_i32 s57, 0, 0x10100
	s_add_i32 s62, 0, 0x18180
	s_mov_b32 s63, 0x800000
	s_add_i32 s73, 0, 0x14800
	s_mov_b32 s89, 0x7060302
	s_add_i32 s0, 0, 0x14000
	s_mov_b32 s1, 0x42ddb3d8
	s_mov_b32 s72, 0x3dd53b94
	s_mov_b32 s64, 0xc000
	s_add_i32 s65, 0, 0x27f44
	v_mov_b32_e32 v195, 1
	v_mov_b32_e32 v196, s94
	v_mov_b32_e32 v220, v161
	v_mov_b32_e32 v221, v161
	v_mov_b32_e32 v222, v161
	v_mov_b32_e32 v223, v161
	v_mbcnt_hi_u32_b32 v197, -1, v0
	v_mov_b32_e32 v198, 0xf149f2ca
	s_mov_b32 s99, 0
	s_branch .LBB0_1840

.LBB0_1840:
	s_and_saveexec_b64 s[4:5], s[2:3]
	s_cbranch_execz .LBB0_1844
	s_mov_b64 s[10:11], exec
	v_mbcnt_lo_u32_b32 v0, s10, 0
	v_mbcnt_hi_u32_b32 v0, s11, v0
	v_cmp_eq_u32_e32 vcc, 0, v0
	s_and_saveexec_b64 s[6:7], vcc
	s_cbranch_execz .LBB0_1843
	s_cmp_eq_u32 s99, 0
	s_cbranch_scc1 .Lq_first
	s_bcnt1_i32_b64 s8, s[10:11]
	v_mov_b32_e32 v1, s8
	global_atomic_add v1, v161, v1, s[36:37] offset:256 sc0
	s_branch .LBB0_1843
.Lq_first:
	v_readlane_b32 s8, v255, 2
	s_add_i32 s8, s8, 0xffffff00
	v_mov_b32_e32 v1, s8
.LBB0_1843:
	s_or_b64 exec, exec, s[6:7]
	s_waitcnt vmcnt(0)
	v_readfirstlane_b32 s6, v1
	v_mov_b32_e32 v1, s94
	s_nop 0
	v_add_u32_e32 v0, s6, v0
	v_add_u32_e32 v0, 0x100, v0
	ds_write_b32 v1, v0
.LBB0_1844:
	s_or_b64 exec, exec, s[4:5]
	s_waitcnt vmcnt(0) lgkmcnt(0)
	s_barrier
	ds_read_b32 v0, v196
	s_mov_b64 s[4:5], -1
	s_waitcnt lgkmcnt(0)
	s_barrier
	v_readfirstlane_b32 s34, v0
	s_mov_b32 s99, 1
	s_cmpk_gt_i32 s34, 0x3ff
	s_cbranch_scc1 .LBB0_1839
	s_cmpk_lt_i32 s34, 0x100
	s_cselect_b64 s[4:5], -1, 0
	s_cmpk_gt_i32 s34, 0xff
	s_cselect_b64 s[6:7], -1, 0
	s_mov_b32 s8, 0
	s_and_b64 vcc, exec, s[4:5]
	s_cbranch_vccnz .LBB0_1848
	s_cmpk_lt_u32 s34, 0x180
	s_mov_b32 s8, 1
	s_cbranch_scc1 .LBB0_1848
	s_cmpk_lt_u32 s34, 0x200
	s_cselect_b32 s8, 3, 4
	s_cmpk_gt_u32 s34, 0x1bf
	s_cselect_b32 s8, s8, 2

	.amdhsa_kernel _Z10fwd_kernel4Args
		.amdhsa_group_segment_fixed_size 0
		.amdhsa_private_segment_fixed_size 0
		.amdhsa_kernarg_size 592
		.amdhsa_user_sgpr_count 2
		.amdhsa_user_sgpr_dispatch_ptr 0
		.amdhsa_user_sgpr_queue_ptr 0
		.amdhsa_user_sgpr_kernarg_segment_ptr 1
		.amdhsa_user_sgpr_dispatch_id 0
		.amdhsa_user_sgpr_kernarg_preload_length 0
		.amdhsa_user_sgpr_kernarg_preload_offset 0
		.amdhsa_user_sgpr_private_segment_size 0
		.amdhsa_uses_dynamic_stack 0
		.amdhsa_enable_private_segment 0
		.amdhsa_system_sgpr_workgroup_id_x 1
		.amdhsa_system_sgpr_workgroup_id_y 0
		.amdhsa_system_sgpr_workgroup_id_z 0
		.amdhsa_system_sgpr_workgroup_info 0
		.amdhsa_system_vgpr_workitem_id 0
		.amdhsa_next_free_vgpr 256
		.amdhsa_next_free_sgpr 100
		.amdhsa_accum_offset 256
		.amdhsa_reserve_vcc 1
		.amdhsa_float_round_mode_32 0
		.amdhsa_float_round_mode_16_64 0
		.amdhsa_float_denorm_mode_32 3
		.amdhsa_float_denorm_mode_16_64 3
		.amdhsa_dx10_clamp 1
		.amdhsa_ieee_mode 1
		.amdhsa_fp16_overflow 0
		.amdhsa_tg_split 0
		.amdhsa_exception_fp_ieee_invalid_op 0
		.amdhsa_exception_fp_denorm_src 0
		.amdhsa_exception_fp_ieee_div_zero 0
		.amdhsa_exception_fp_ieee_overflow 0
		.amdhsa_exception_fp_ieee_underflow 0
		.amdhsa_exception_fp_ieee_inexact 0
		.amdhsa_exception_int_div_zero 0
	.end_amdhsa_kernel

amdhsa.kernels:
  - .agpr_count:     0
    .args:
      - .offset:         0
        .size:           336
        .value_kind:     by_value
      - .offset:         336
        .size:           4
        .value_kind:     hidden_block_count_x
      - .offset:         340
        .size:           4
        .value_kind:     hidden_block_count_y
      - .offset:         344
        .size:           4
        .value_kind:     hidden_block_count_z
      - .offset:         348
        .size:           2
        .value_kind:     hidden_group_size_x
      - .offset:         350
        .size:           2
        .value_kind:     hidden_group_size_y
      - .offset:         352
        .size:           2
        .value_kind:     hidden_group_size_z
      - .offset:         354
        .size:           2
        .value_kind:     hidden_remainder_x
      - .offset:         356
        .size:           2
        .value_kind:     hidden_remainder_y
      - .offset:         358
        .size:           2
        .value_kind:     hidden_remainder_z
      - .offset:         376
        .size:           8
        .value_kind:     hidden_global_offset_x
      - .offset:         384
        .size:           8
        .value_kind:     hidden_global_offset_y
      - .offset:         392
        .size:           8
        .value_kind:     hidden_global_offset_z
      - .offset:         400
        .size:           2
        .value_kind:     hidden_grid_dims
      - .offset:         456
        .size:           4
        .value_kind:     hidden_dynamic_lds_size
    .group_segment_fixed_size: 0
    .kernarg_segment_align: 8
    .kernarg_segment_size: 592
    .language:       OpenCL C
    .language_version:
      - 2
      - 0
    .max_flat_workgroup_size: 512
    .name:           _Z10fwd_kernel4Args
    .private_segment_fixed_size: 0
    .sgpr_count:     106
    .sgpr_spill_count: 133
    .symbol:         _Z10fwd_kernel4Args.kd
    .uniform_work_group_size: 1
    .uses_dynamic_stack: false
    .vgpr_count:     256
    .vgpr_spill_count: 0
    .wavefront_size: 64
